# v20 + attention prompt unit: the 8 Q loads issued before the V staging into spare registers, copied after the barrier
# speedup vs baseline: 1.0069x; 1.0069x over previous
.LBB0_186:
	s_or_b64 exec, exec, s[0:1]
	v_readlane_b32 s17, v254, 41
	v_readlane_b32 s18, v254, 32
	v_readlane_b32 s19, v254, 33
	v_lshlrev_b32_e32 v208, 4, v69
	v_mov_b32_e32 v209, 0
	s_lshl_b32 s16, s10, 2
	s_add_i32 s16, s16, s17
	s_lshl_b32 s16, s16, 7
	s_mov_b32 s17, 0
	v_mov_b64_e32 v[178:179], s[18:19]
	v_or_b32_e32 v176, s78, v106
	v_or_b32_e32 v176, s88, v176
	v_mad_u64_u32 v[176:177], s[20:21], v176, s95, v[178:179]
	v_mad_i32_i24 v177, s79, v210, v177
	v_lshl_add_u64 v[176:177], v[176:177], 0, s[16:17]
	v_lshl_add_u64 v[176:177], v[176:177], 0, v[208:209]
	global_load_dwordx4 v[200:203], v[176:177], off offset:2112
	global_load_dwordx4 v[204:207], v[176:177], off offset:2048
	v_or_b32_e32 v176, s78, v106
	v_or_b32_e32 v176, s89, v176
	v_mad_u64_u32 v[176:177], s[20:21], v176, s95, v[178:179]
	v_mad_i32_i24 v177, s79, v210, v177
	v_lshl_add_u64 v[176:177], v[176:177], 0, s[16:17]
	v_lshl_add_u64 v[176:177], v[176:177], 0, v[208:209]
	global_load_dwordx4 v[228:231], v[176:177], off offset:2112
	global_load_dwordx4 v[232:235], v[176:177], off offset:2048
	v_or_b32_e32 v176, s78, v106
	v_or_b32_e32 v176, s90, v176
	v_mad_u64_u32 v[176:177], s[20:21], v176, s95, v[178:179]
	v_mad_i32_i24 v177, s79, v210, v177
	v_lshl_add_u64 v[176:177], v[176:177], 0, s[16:17]
	v_lshl_add_u64 v[176:177], v[176:177], 0, v[208:209]
	global_load_dwordx4 v[236:239], v[176:177], off offset:2112
	global_load_dwordx4 v[248:251], v[176:177], off offset:2048
	v_or_b32_e32 v176, s78, v106
	v_or_b32_e32 v176, s91, v176
	v_mad_u64_u32 v[176:177], s[20:21], v176, s95, v[178:179]
	v_mad_i32_i24 v177, s79, v210, v177
	v_lshl_add_u64 v[176:177], v[176:177], 0, s[16:17]
	v_lshl_add_u64 v[176:177], v[176:177], 0, v[208:209]
	global_load_dwordx4 v[214:217], v[176:177], off offset:2112
	global_load_dwordx4 v[196:199], v[176:177], off offset:2048
	v_and_b32_e32 v0, 0xff, v88
	s_movk_i32 s0, 0x7f
	v_ashrrev_i32_e32 v2, 8, v88
	v_cmp_lt_u32_e64 s[0:1], s0, v0
	s_nor_b64 s[8:9], s[4:5], s[0:1]
	v_lshlrev_b32_e32 v34, 5, v2
	s_and_saveexec_b64 s[12:13], s[8:9]
	s_xor_b64 s[8:9], exec, s[12:13]
	v_lshlrev_b32_e32 v34, 5, v2
	s_or_saveexec_b64 s[8:9], s[8:9]
	v_mov_b32_e32 v9, 0
	v_mov_b32_e32 v8, 0
	v_mov_b32_e32 v7, 0
	v_mov_b32_e32 v6, 0
	v_mov_b32_e32 v21, 0
	v_mov_b32_e32 v20, 0
	v_mov_b32_e32 v19, 0
	v_mov_b32_e32 v18, 0
	v_mov_b32_e32 v5, 0
	v_mov_b32_e32 v4, 0
	v_mov_b32_e32 v3, 0
	v_mov_b32_e32 v2, 0
	v_mov_b32_e32 v13, 0
	v_mov_b32_e32 v12, 0
	v_mov_b32_e32 v11, 0
	v_mov_b32_e32 v10, 0
	v_mov_b32_e32 v17, 0
	v_mov_b32_e32 v16, 0
	v_mov_b32_e32 v15, 0
	v_mov_b32_e32 v14, 0
	v_mov_b32_e32 v25, 0
	v_mov_b32_e32 v24, 0
	v_mov_b32_e32 v23, 0
	v_mov_b32_e32 v22, 0
	v_mov_b32_e32 v29, 0
	v_mov_b32_e32 v28, 0
	v_mov_b32_e32 v27, 0
	v_mov_b32_e32 v26, 0
	v_mov_b32_e32 v33, 0
	v_mov_b32_e32 v32, 0
	v_mov_b32_e32 v31, 0
	v_mov_b32_e32 v30, 0
	s_xor_b64 exec, exec, s[8:9]
	s_cbranch_execz .LBB0_190
	s_add_u32 s12, s78, 0xffffff80
	s_addc_u32 s13, s79, -1
	v_lshl_add_u64 v[2:3], s[12:13], 0, v[0:1]
	v_readlane_b32 s12, v254, 32
	v_readlane_b32 s13, v254, 33
	s_lshl_b32 s92, s10, 7
	v_ashrrev_i32_e32 v35, 31, v34
	v_mov_b64_e32 v[4:5], s[12:13]
	v_mad_u64_u32 v[4:5], s[12:13], v2, s95, v[4:5]
	v_mad_i32_i24 v5, v3, s95, v5
	v_lshl_add_u64 v[2:3], v[4:5], 0, s[92:93]
	v_lshl_add_u64 v[10:11], v[34:35], 1, v[2:3]
	s_mov_b64 s[12:13], 0x1200
	s_movk_i32 s3, 0x1000
	v_lshl_add_u64 v[12:13], v[10:11], 0, s[12:13]
	v_add_co_u32_e32 v10, vcc, s3, v10
	v_mov_b64_e32 v[2:3], v[184:185]
	v_mov_b64_e32 v[4:5], v[186:187]
	v_mov_b64_e32 v[6:7], v[188:189]
	v_mov_b64_e32 v[8:9], v[190:191]
	v_addc_co_u32_e32 v11, vcc, 0, v11, vcc
	v_mov_b64_e32 v[18:19], v[180:181]
	v_mov_b64_e32 v[20:21], v[182:183]
	v_mov_b64_e32 v[36:37], v[192:193]
	v_mov_b64_e32 v[38:39], v[194:195]
	v_lshlrev_b32_e32 v22, 16, v2
	v_and_b32_e32 v23, 0xffff0000, v2
	v_lshlrev_b32_e32 v24, 16, v3
	v_and_b32_e32 v25, 0xffff0000, v3
	v_lshlrev_b32_e32 v14, 16, v4
	v_and_b32_e32 v15, 0xffff0000, v4
	v_lshlrev_b32_e32 v16, 16, v5
	v_and_b32_e32 v17, 0xffff0000, v5
	v_lshlrev_b32_e32 v10, 16, v6
	v_and_b32_e32 v11, 0xffff0000, v6
	v_lshlrev_b32_e32 v12, 16, v7
	v_and_b32_e32 v13, 0xffff0000, v7
	v_lshlrev_b32_e32 v2, 16, v8
	v_and_b32_e32 v3, 0xffff0000, v8
	v_lshlrev_b32_e32 v4, 16, v9
	v_and_b32_e32 v5, 0xffff0000, v9
	v_lshlrev_b32_e32 v30, 16, v18
	v_and_b32_e32 v31, 0xffff0000, v18
	v_lshlrev_b32_e32 v32, 16, v19
	v_and_b32_e32 v33, 0xffff0000, v19
	v_lshlrev_b32_e32 v26, 16, v20
	v_and_b32_e32 v27, 0xffff0000, v20
	v_lshlrev_b32_e32 v28, 16, v21
	v_and_b32_e32 v29, 0xffff0000, v21
	v_lshlrev_b32_e32 v18, 16, v36
	v_and_b32_e32 v19, 0xffff0000, v36
	v_lshlrev_b32_e32 v20, 16, v37
	v_and_b32_e32 v21, 0xffff0000, v37
	v_lshlrev_b32_e32 v6, 16, v38
	v_and_b32_e32 v7, 0xffff0000, v38
	v_lshlrev_b32_e32 v8, 16, v39
	v_and_b32_e32 v9, 0xffff0000, v39

.LBB0_192:
	s_or_b64 exec, exec, s[0:1]
	v_readlane_b32 s2, v254, 32
	s_lshl_b32 s0, s10, 2
	v_readlane_b32 s1, v254, 41
	v_readlane_b32 s3, v254, 33
	v_lshlrev_b32_e32 v96, 3, v69
	v_ashrrev_i32_e32 v97, 31, v96
	v_lshlrev_b64 v[6:7], 1, v[96:97]
	v_lshlrev_b32_e32 v50, 2, v69
	v_xor_b32_e32 v77, 32, v211
	v_or_b32_e32 v51, 0x80, v106
	v_lshl_add_u32 v4, v88, 2, 0
	v_or_b32_e32 v5, s78, v106
	s_add_i32 s0, s0, s1
	v_mov_b64_e32 v[2:3], s[2:3]
	v_add_u32_e32 v12, 0x11c00, v4
	v_or_b32_e32 v4, s88, v5
	v_or_b32_e32 v8, s89, v5
	v_or_b32_e32 v10, s90, v5
	v_or_b32_e32 v13, s91, v5
	s_lshl_b32 s2, s0, 6
	v_mad_u64_u32 v[4:5], s[6:7], v4, s95, v[2:3]
	v_mad_u64_u32 v[8:9], s[6:7], v8, s95, v[2:3]
	v_mad_u64_u32 v[10:11], s[6:7], v10, s95, v[2:3]
	v_mad_u64_u32 v[2:3], s[6:7], v13, s95, v[2:3]
	s_ashr_i32 s3, s2, 31
	v_mad_i32_i24 v5, s79, v210, v5
	v_mad_i32_i24 v9, s79, v210, v9
	v_mad_i32_i24 v11, s79, v210, v11
	s_lshl_b64 s[6:7], s[2:3], 1
	v_mad_i32_i24 v3, s79, v210, v3
	v_lshl_add_u64 v[4:5], v[4:5], 0, s[6:7]
	v_lshl_add_u64 v[8:9], v[8:9], 0, s[6:7]
	v_lshl_add_u64 v[10:11], v[10:11], 0, s[6:7]
	v_lshl_add_u64 v[2:3], v[2:3], 0, s[6:7]
	v_lshl_add_u64 v[4:5], v[4:5], 0, v[6:7]
	v_lshl_add_u64 v[8:9], v[8:9], 0, v[6:7]
	v_lshl_add_u64 v[10:11], v[10:11], 0, v[6:7]
	v_lshl_add_u64 v[2:3], v[2:3], 0, v[6:7]
	v_readlane_b32 s1, v253, 22
	s_waitcnt vmcnt(8)
	ds_write_b32 v12, v175
	s_waitcnt lgkmcnt(0)
	s_barrier
	v_mov_b32_e32 v0, s1
	v_readlane_b32 s1, v253, 23
	v_xor_b32_e32 v2, 16, v211
	v_cmp_lt_i32_e32 vcc, v2, v76
	v_mov_b32_e32 v4, s1
	s_ashr_i32 s1, s0, 31
	v_cndmask_b32_e32 v6, v211, v2, vcc
	ds_read_b64 v[2:3], v0
	ds_read_b64 v[4:5], v4
	s_lshl_b64 s[0:1], s[0:1], 2
	v_lshlrev_b32_e32 v107, 2, v6
	v_cmp_lt_i32_e32 vcc, v77, v76
	s_waitcnt lgkmcnt(1)
	v_lshl_add_u64 v[2:3], v[2:3], 0, s[0:1]
	s_waitcnt lgkmcnt(0)
	v_lshl_add_u64 v[14:15], v[96:97], 2, v[4:5]
	global_load_dword v97, v[2:3], off
	s_nop 0
	global_load_dwordx4 v[2:5], v[14:15], off offset:144
	global_load_dwordx4 v[10:13], v[14:15], off offset:128
	global_load_dwordx4 v[6:9], v[14:15], off offset:16
	s_nop 0
	global_load_dwordx4 v[14:17], v[14:15], off
	v_cndmask_b32_e32 v0, v211, v77, vcc
	s_waitcnt vmcnt(5)
	v_mov_b64_e32 v[34:35], v[200:201]
	v_mov_b64_e32 v[36:37], v[202:203]
	v_mov_b64_e32 v[38:39], v[228:229]
	v_mov_b64_e32 v[40:41], v[230:231]
	v_mov_b64_e32 v[42:43], v[236:237]
	v_mov_b64_e32 v[44:45], v[238:239]
	v_mov_b64_e32 v[46:47], v[214:215]
	v_mov_b64_e32 v[48:49], v[216:217]
	v_mov_b64_e32 v[30:31], v[204:205]
	v_mov_b64_e32 v[32:33], v[206:207]
	v_mov_b64_e32 v[26:27], v[232:233]
	v_mov_b64_e32 v[28:29], v[234:235]
	v_mov_b64_e32 v[22:23], v[248:249]
	v_mov_b64_e32 v[24:25], v[250:251]
	v_mov_b64_e32 v[18:19], v[196:197]
	v_mov_b64_e32 v[20:21], v[198:199]
	s_waitcnt vmcnt(9)
	v_lshlrev_b32_e32 v52, 16, v49
	v_lshlrev_b32_e32 v104, 16, v37
	v_and_b32_e32 v105, 0xffff0000, v37
	v_lshlrev_b32_e32 v86, 16, v41
	v_and_b32_e32 v87, 0xffff0000, v41
	s_waitcnt vmcnt(8)
	v_lshlrev_b32_e32 v100, 16, v33
	v_and_b32_e32 v101, 0xffff0000, v33
	s_waitcnt vmcnt(6)
	v_lshlrev_b32_e32 v64, 16, v25
	v_and_b32_e32 v65, 0xffff0000, v25
	v_lshlrev_b32_e32 v102, 16, v36
	v_and_b32_e32 v103, 0xffff0000, v36
	v_lshlrev_b32_e32 v82, 16, v40
	v_and_b32_e32 v83, 0xffff0000, v40
	v_lshlrev_b32_e32 v36, 16, v32
	v_and_b32_e32 v37, 0xffff0000, v32
	v_lshlrev_b32_e32 v70, 16, v24
	v_and_b32_e32 v71, 0xffff0000, v24
	v_lshlrev_b32_e32 v24, 16, v35
	v_and_b32_e32 v25, 0xffff0000, v35
	v_lshlrev_b32_e32 v88, 16, v39
	v_and_b32_e32 v89, 0xffff0000, v39
	v_lshlrev_b32_e32 v74, 16, v43
	v_and_b32_e32 v75, 0xffff0000, v43
	v_lshlrev_b32_e32 v32, 16, v34
	v_and_b32_e32 v33, 0xffff0000, v34
	v_lshlrev_b32_e32 v92, 16, v38
	v_and_b32_e32 v93, 0xffff0000, v38
	v_lshlrev_b32_e32 v62, 16, v42
	v_and_b32_e32 v63, 0xffff0000, v42
	v_lshlrev_b32_e32 v42, 16, v46
	v_and_b32_e32 v43, 0xffff0000, v46
	v_lshlrev_b32_e32 v60, 16, v45
	v_and_b32_e32 v61, 0xffff0000, v45
	v_and_b32_e32 v53, 0xffff0000, v49
	v_lshlrev_b32_e32 v80, 16, v29
	v_and_b32_e32 v81, 0xffff0000, v29
	s_waitcnt vmcnt(5)
	v_lshlrev_b32_e32 v54, 16, v21
	v_and_b32_e32 v55, 0xffff0000, v21
	v_lshlrev_b32_e32 v68, 16, v44
	v_and_b32_e32 v69, 0xffff0000, v44
	v_lshlrev_b32_e32 v44, 16, v48
	v_and_b32_e32 v45, 0xffff0000, v48
	v_lshlrev_b32_e32 v84, 16, v28
	v_and_b32_e32 v85, 0xffff0000, v28
	v_lshlrev_b32_e32 v48, 16, v20
	v_and_b32_e32 v49, 0xffff0000, v20
	v_lshlrev_b32_e32 v56, 16, v47
	v_and_b32_e32 v57, 0xffff0000, v47
	v_lshlrev_b32_e32 v28, 16, v31
	v_and_b32_e32 v29, 0xffff0000, v31
	v_lshlrev_b32_e32 v90, 16, v27
	v_and_b32_e32 v91, 0xffff0000, v27
	v_lshlrev_b32_e32 v58, 16, v19
	v_and_b32_e32 v59, 0xffff0000, v19
	v_lshlrev_b32_e32 v34, 16, v30
	v_and_b32_e32 v35, 0xffff0000, v30
	v_lshlrev_b32_e32 v94, 16, v26
	v_and_b32_e32 v95, 0xffff0000, v26
	v_lshlrev_b32_e32 v72, 16, v22
	v_and_b32_e32 v73, 0xffff0000, v22
	v_lshlrev_b32_e32 v46, 16, v18
	v_and_b32_e32 v47, 0xffff0000, v18
	v_pk_mul_f32 v[18:19], v[104:105], v[104:105]
	v_pk_mul_f32 v[20:21], v[86:87], v[86:87]
	v_pk_mul_f32 v[30:31], v[102:103], v[102:103]
	v_pk_mul_f32 v[38:39], v[82:83], v[82:83]
	v_pk_mul_f32 v[98:99], v[24:25], v[24:25]
	v_pk_mul_f32 v[108:109], v[88:89], v[88:89]
	v_pk_mul_f32 v[114:115], v[32:33], v[32:33]
	v_pk_mul_f32 v[116:117], v[92:93], v[92:93]
	v_pk_mul_f32 v[118:119], v[62:63], v[62:63]
	v_pk_mul_f32 v[120:121], v[42:43], v[42:43]
	v_lshlrev_b32_e32 v66, 16, v23
	v_and_b32_e32 v67, 0xffff0000, v23
	v_pk_mul_f32 v[22:23], v[60:61], v[60:61]
	v_pk_mul_f32 v[26:27], v[52:53], v[52:53]
	v_pk_mul_f32 v[40:41], v[68:69], v[68:69]
	v_pk_mul_f32 v[78:79], v[44:45], v[44:45]
	v_pk_mul_f32 v[110:111], v[74:75], v[74:75]
	v_pk_mul_f32 v[112:113], v[56:57], v[56:57]
	v_pk_fma_f32 v[18:19], v[100:101], v[100:101], v[18:19]
	v_pk_fma_f32 v[20:21], v[80:81], v[80:81], v[20:21]
	v_pk_fma_f32 v[30:31], v[36:37], v[36:37], v[30:31]
	v_pk_fma_f32 v[38:39], v[84:85], v[84:85], v[38:39]
	v_pk_fma_f32 v[98:99], v[28:29], v[28:29], v[98:99]
	v_pk_fma_f32 v[108:109], v[90:91], v[90:91], v[108:109]
	v_pk_fma_f32 v[114:115], v[34:35], v[34:35], v[114:115]
	v_pk_fma_f32 v[116:117], v[94:95], v[94:95], v[116:117]
	v_pk_fma_f32 v[118:119], v[72:73], v[72:73], v[118:119]
	v_pk_fma_f32 v[120:121], v[46:47], v[46:47], v[120:121]
	v_pk_fma_f32 v[22:23], v[64:65], v[64:65], v[22:23]
	v_pk_fma_f32 v[26:27], v[54:55], v[54:55], v[26:27]
	v_pk_fma_f32 v[40:41], v[70:71], v[70:71], v[40:41]
	v_pk_fma_f32 v[78:79], v[48:49], v[48:49], v[78:79]
	v_pk_fma_f32 v[110:111], v[66:67], v[66:67], v[110:111]
	v_pk_fma_f32 v[112:113], v[58:59], v[58:59], v[112:113]
	v_mov_b32_e32 v122, v116
	v_mov_b32_e32 v123, v114
	v_mov_b32_e32 v114, v117
	v_mov_b32_e32 v116, v108
	v_mov_b32_e32 v117, v98
	v_mov_b32_e32 v98, v109
	v_mov_b32_e32 v108, v38
	v_mov_b32_e32 v109, v30
	v_mov_b32_e32 v30, v39
	v_mov_b32_e32 v38, v20
	v_mov_b32_e32 v39, v18
	v_mov_b32_e32 v18, v21
	v_mov_b32_e32 v20, v120
	v_mov_b32_e32 v21, v118
	v_mov_b32_e32 v118, v121
	v_mov_b32_e32 v120, v112
	v_mov_b32_e32 v121, v110
	v_mov_b32_e32 v110, v113
	v_mov_b32_e32 v112, v78
	v_mov_b32_e32 v113, v40
	v_mov_b32_e32 v40, v79
	v_mov_b32_e32 v78, v26
	v_mov_b32_e32 v79, v22
	v_mov_b32_e32 v22, v27
	v_pk_add_f32 v[26:27], v[122:123], v[114:115]
	v_pk_add_f32 v[20:21], v[20:21], v[118:119]
	v_pk_add_f32 v[26:27], v[116:117], v[26:27]
	v_pk_add_f32 v[20:21], v[120:121], v[20:21]
	v_pk_add_f32 v[26:27], v[98:99], v[26:27]
	v_pk_add_f32 v[20:21], v[110:111], v[20:21]
	v_pk_add_f32 v[26:27], v[108:109], v[26:27]
	v_pk_add_f32 v[20:21], v[112:113], v[20:21]
	v_pk_add_f32 v[26:27], v[30:31], v[26:27]
	v_pk_add_f32 v[20:21], v[40:41], v[20:21]
	v_pk_add_f32 v[26:27], v[38:39], v[26:27]
	v_pk_add_f32 v[20:21], v[78:79], v[20:21]
	v_pk_add_f32 v[18:19], v[18:19], v[26:27]
	v_pk_add_f32 v[20:21], v[22:23], v[20:21]
	ds_bpermute_b32 v23, v107, v19
	ds_bpermute_b32 v22, v107, v18
	ds_bpermute_b32 v27, v107, v21
	ds_bpermute_b32 v26, v107, v20
	v_lshlrev_b32_e32 v108, 2, v0
	v_sub_u32_e32 v0, v51, v50
	s_waitcnt lgkmcnt(2)
	v_pk_add_f32 v[18:19], v[18:19], v[22:23]
	v_cmp_gt_u32_e32 vcc, s94, v0
	s_waitcnt lgkmcnt(0)
	v_pk_add_f32 v[76:77], v[20:21], v[26:27]
	ds_bpermute_b32 v21, v108, v19
	ds_bpermute_b32 v20, v108, v18
	ds_bpermute_b32 v79, v108, v77
	ds_bpermute_b32 v78, v108, v76
	v_mov_b32_e32 v109, 0xf1c9f2ca
	v_sub_u32_e32 v22, v106, v50
	v_mov_b32_e32 v110, 0xf1c9f2ca
	s_and_saveexec_b64 s[0:1], vcc
	v_sub_u32_e32 v23, v106, v50
	v_lshl_add_u32 v23, v23, 2, s96
	ds_read_b32 v110, v23 offset:512
	s_or_b64 exec, exec, s[0:1]
	v_not_b32_e32 v23, v50
	v_add_u32_e32 v26, v51, v23
	v_cmp_gt_u32_e32 vcc, s94, v26
	s_and_saveexec_b64 s[0:1], vcc
	v_add_u32_e32 v23, v106, v23
	v_lshl_add_u32 v23, v23, 2, s96
	ds_read_b32 v109, v23 offset:512
	s_or_b64 exec, exec, s[0:1]
	v_or_b32_e32 v23, 2, v50
	v_sub_u32_e32 v26, v51, v23
	v_cmp_gt_u32_e32 vcc, s94, v26
	v_mov_b32_e32 v111, 0xf1c9f2ca
	v_mov_b32_e32 v112, 0xf1c9f2ca
	s_and_saveexec_b64 s[0:1], vcc
	v_sub_u32_e32 v23, v106, v23
	v_lshl_add_u32 v23, v23, 2, s96
	ds_read_b32 v112, v23 offset:512
	s_or_b64 exec, exec, s[0:1]
	v_or_b32_e32 v23, 3, v50
	v_sub_u32_e32 v26, v51, v23
	v_cmp_gt_u32_e32 vcc, s94, v26
	s_and_saveexec_b64 s[0:1], vcc
	v_sub_u32_e32 v23, v106, v23
	v_lshl_add_u32 v23, v23, 2, s96
	ds_read_b32 v111, v23 offset:512
	s_or_b64 exec, exec, s[0:1]
	v_add_u32_e32 v23, -16, v0
	v_cmp_gt_u32_e32 vcc, s94, v23
	v_mov_b32_e32 v113, 0xf1c9f2ca
	v_mov_b32_e32 v114, 0xf1c9f2ca
	s_and_saveexec_b64 s[0:1], vcc
	v_sub_u32_e32 v23, v106, v50
	v_lshl_add_u32 v23, v23, 2, s96
	ds_read_b32 v114, v23 offset:448
	s_or_b64 exec, exec, s[0:1]
	v_subrev_u32_e32 v23, 17, v0
	v_cmp_gt_u32_e32 vcc, s94, v23
	s_and_saveexec_b64 s[0:1], vcc
	v_sub_u32_e32 v23, v106, v50
	v_lshl_add_u32 v23, v23, 2, s96
	ds_read_b32 v113, v23 offset:444
	s_or_b64 exec, exec, s[0:1]
	v_subrev_u32_e32 v23, 18, v0
	v_cmp_gt_u32_e32 vcc, s94, v23
	v_mov_b32_e32 v115, 0xf1c9f2ca
	v_mov_b32_e32 v116, 0xf1c9f2ca
	s_and_saveexec_b64 s[0:1], vcc
	v_sub_u32_e32 v23, v106, v50
	v_lshl_add_u32 v23, v23, 2, s96
	ds_read_b32 v116, v23 offset:440
	s_or_b64 exec, exec, s[0:1]
	v_subrev_u32_e32 v23, 19, v0
	v_cmp_gt_u32_e32 vcc, s94, v23
	s_and_saveexec_b64 s[0:1], vcc
	v_sub_u32_e32 v23, v106, v50
	v_lshl_add_u32 v23, v23, 2, s96
	ds_read_b32 v115, v23 offset:436
	s_or_b64 exec, exec, s[0:1]
	v_subrev_u32_e32 v23, 32, v0
	v_cmp_gt_u32_e32 vcc, s94, v23
	v_mov_b32_e32 v117, 0xf1c9f2ca
	v_mov_b32_e32 v118, 0xf1c9f2ca
	s_and_saveexec_b64 s[0:1], vcc
	v_sub_u32_e32 v23, v106, v50
	v_lshl_add_u32 v23, v23, 2, s96
	ds_read_b32 v118, v23 offset:384
	s_or_b64 exec, exec, s[0:1]
	v_subrev_u32_e32 v23, 33, v0
	v_cmp_gt_u32_e32 vcc, s94, v23
	s_and_saveexec_b64 s[0:1], vcc
	v_sub_u32_e32 v23, v106, v50
	v_lshl_add_u32 v23, v23, 2, s96
	ds_read_b32 v117, v23 offset:380
	s_or_b64 exec, exec, s[0:1]
	v_subrev_u32_e32 v23, 34, v0
	v_cmp_gt_u32_e32 vcc, s94, v23
	v_mov_b32_e32 v119, 0xf1c9f2ca
	v_mov_b32_e32 v120, 0xf1c9f2ca
	s_and_saveexec_b64 s[0:1], vcc
	v_sub_u32_e32 v23, v106, v50
	v_lshl_add_u32 v23, v23, 2, s96
	ds_read_b32 v120, v23 offset:376
	s_or_b64 exec, exec, s[0:1]
	v_subrev_u32_e32 v23, 35, v0
	v_cmp_gt_u32_e32 vcc, s94, v23
	s_and_saveexec_b64 s[0:1], vcc
	v_sub_u32_e32 v23, v106, v50
	v_lshl_add_u32 v23, v23, 2, s96
	ds_read_b32 v119, v23 offset:372
	s_or_b64 exec, exec, s[0:1]
	v_subrev_u32_e32 v23, 48, v0
	v_cmp_gt_u32_e32 vcc, s94, v23
	v_mov_b32_e32 v121, 0xf1c9f2ca
	v_mov_b32_e32 v122, 0xf1c9f2ca
	s_and_saveexec_b64 s[0:1], vcc
	v_sub_u32_e32 v23, v106, v50
	v_lshl_add_u32 v23, v23, 2, s96
	ds_read_b32 v122, v23 offset:320
	s_or_b64 exec, exec, s[0:1]
	v_subrev_u32_e32 v23, 49, v0
	v_cmp_gt_u32_e32 vcc, s94, v23
	s_and_saveexec_b64 s[0:1], vcc
	v_sub_u32_e32 v23, v106, v50
	v_lshl_add_u32 v23, v23, 2, s96
	ds_read_b32 v121, v23 offset:316
	s_or_b64 exec, exec, s[0:1]
	v_subrev_u32_e32 v23, 50, v0
	v_cmp_gt_u32_e32 vcc, s94, v23
	v_mov_b32_e32 v123, 0xf1c9f2ca
	v_mov_b32_e32 v124, 0xf1c9f2ca
	s_and_saveexec_b64 s[0:1], vcc
	v_sub_u32_e32 v23, v106, v50
	v_lshl_add_u32 v23, v23, 2, s96
	ds_read_b32 v124, v23 offset:312
	s_or_b64 exec, exec, s[0:1]
	v_subrev_u32_e32 v23, 51, v0
	v_cmp_gt_u32_e32 vcc, s94, v23
	s_and_saveexec_b64 s[0:1], vcc
	v_sub_u32_e32 v23, v106, v50
	v_lshl_add_u32 v23, v23, 2, s96
	ds_read_b32 v123, v23 offset:308
	s_or_b64 exec, exec, s[0:1]
	v_subrev_u32_e32 v23, 64, v0
	v_cmp_gt_u32_e32 vcc, s94, v23
	v_mov_b32_e32 v125, 0xf1c9f2ca
	v_mov_b32_e32 v126, 0xf1c9f2ca
	s_and_saveexec_b64 s[0:1], vcc
	v_sub_u32_e32 v23, v106, v50
	v_lshl_add_u32 v23, v23, 2, s96
	ds_read_b32 v126, v23 offset:256
	s_or_b64 exec, exec, s[0:1]
	v_add_u32_e32 v23, 0xffffffbf, v0
	v_cmp_gt_u32_e32 vcc, s94, v23
	s_and_saveexec_b64 s[0:1], vcc
	v_sub_u32_e32 v23, v106, v50
	v_lshl_add_u32 v23, v23, 2, s96
	ds_read_b32 v125, v23 offset:252
	s_or_b64 exec, exec, s[0:1]
	v_add_u32_e32 v23, 0xffffffbe, v0
	v_cmp_gt_u32_e32 vcc, s94, v23
	v_mov_b32_e32 v127, 0xf1c9f2ca
	v_mov_b32_e32 v128, 0xf1c9f2ca
	s_and_saveexec_b64 s[0:1], vcc
	v_sub_u32_e32 v23, v106, v50
	v_lshl_add_u32 v23, v23, 2, s96
	ds_read_b32 v128, v23 offset:248
	s_or_b64 exec, exec, s[0:1]
	v_add_u32_e32 v23, 0xffffffbd, v0
	v_cmp_gt_u32_e32 vcc, s94, v23
	s_and_saveexec_b64 s[0:1], vcc
	v_sub_u32_e32 v23, v106, v50
	v_lshl_add_u32 v23, v23, 2, s96
	ds_read_b32 v127, v23 offset:244
	s_or_b64 exec, exec, s[0:1]
	v_add_u32_e32 v23, 0xffffffb0, v0
	v_cmp_gt_u32_e32 vcc, s94, v23
	v_mov_b32_e32 v129, 0xf1c9f2ca
	v_mov_b32_e32 v130, 0xf1c9f2ca
	s_and_saveexec_b64 s[0:1], vcc
	v_sub_u32_e32 v23, v106, v50
	v_lshl_add_u32 v23, v23, 2, s96
	ds_read_b32 v130, v23 offset:192
	s_or_b64 exec, exec, s[0:1]
	v_add_u32_e32 v23, 0xffffffaf, v0
	v_cmp_gt_u32_e32 vcc, s94, v23
	s_and_saveexec_b64 s[0:1], vcc
	v_sub_u32_e32 v23, v106, v50
	v_lshl_add_u32 v23, v23, 2, s96
	ds_read_b32 v129, v23 offset:188
	s_or_b64 exec, exec, s[0:1]
	v_add_u32_e32 v23, 0xffffffae, v0
	v_cmp_gt_u32_e32 vcc, s94, v23
	v_mov_b32_e32 v131, 0xf1c9f2ca
	v_mov_b32_e32 v132, 0xf1c9f2ca
	s_and_saveexec_b64 s[0:1], vcc
	v_sub_u32_e32 v23, v106, v50
	v_lshl_add_u32 v23, v23, 2, s96
	ds_read_b32 v132, v23 offset:184
	s_or_b64 exec, exec, s[0:1]
	v_add_u32_e32 v23, 0xffffffad, v0
	v_cmp_gt_u32_e32 vcc, s94, v23
	s_and_saveexec_b64 s[0:1], vcc
	v_sub_u32_e32 v23, v106, v50
	v_lshl_add_u32 v23, v23, 2, s96
	ds_read_b32 v131, v23 offset:180
	s_or_b64 exec, exec, s[0:1]
	v_add_u32_e32 v23, 0xffffffa0, v0
	v_cmp_gt_u32_e32 vcc, s94, v23
	v_mov_b32_e32 v133, 0xf1c9f2ca
	v_mov_b32_e32 v134, 0xf1c9f2ca
	s_and_saveexec_b64 s[0:1], vcc
	v_sub_u32_e32 v23, v106, v50
	v_lshl_add_u32 v23, v23, 2, s96
	ds_read_b32 v134, v23 offset:128
	s_or_b64 exec, exec, s[0:1]
	v_add_u32_e32 v23, 0xffffff9f, v0
	v_cmp_gt_u32_e32 vcc, s94, v23
	s_and_saveexec_b64 s[0:1], vcc
	v_sub_u32_e32 v23, v106, v50
	v_lshl_add_u32 v23, v23, 2, s96
	ds_read_b32 v133, v23 offset:124
	s_or_b64 exec, exec, s[0:1]
	v_add_u32_e32 v23, 0xffffff9e, v0
	v_cmp_gt_u32_e32 vcc, s94, v23
	v_mov_b32_e32 v135, 0xf1c9f2ca
	v_mov_b32_e32 v136, 0xf1c9f2ca
	s_and_saveexec_b64 s[0:1], vcc
	v_sub_u32_e32 v23, v106, v50
	v_lshl_add_u32 v23, v23, 2, s96
	ds_read_b32 v136, v23 offset:120
	s_or_b64 exec, exec, s[0:1]
	v_add_u32_e32 v23, 0xffffff9d, v0
	v_cmp_gt_u32_e32 vcc, s94, v23
	s_and_saveexec_b64 s[0:1], vcc
	v_sub_u32_e32 v23, v106, v50
	v_lshl_add_u32 v23, v23, 2, s96
	ds_read_b32 v135, v23 offset:116
	s_or_b64 exec, exec, s[0:1]
	v_add_u32_e32 v23, 0xffffff90, v0
	v_cmp_gt_u32_e32 vcc, s94, v23
	v_mov_b32_e32 v137, 0xf1c9f2ca
	v_mov_b32_e32 v138, 0xf1c9f2ca
	s_and_saveexec_b64 s[0:1], vcc
	v_sub_u32_e32 v23, v106, v50
	v_lshl_add_u32 v23, v23, 2, s96
	ds_read_b32 v138, v23 offset:64
	s_or_b64 exec, exec, s[0:1]
	v_add_u32_e32 v23, 0xffffff8f, v0
	v_cmp_gt_u32_e32 vcc, s94, v23
	s_and_saveexec_b64 s[0:1], vcc
	v_sub_u32_e32 v23, v106, v50
	v_lshl_add_u32 v23, v23, 2, s96
	ds_read_b32 v137, v23 offset:60
	s_or_b64 exec, exec, s[0:1]
	v_add_u32_e32 v23, 0xffffff8e, v0
	v_cmp_gt_u32_e32 vcc, s94, v23
	v_mov_b32_e32 v139, 0xf1c9f2ca
	s_and_saveexec_b64 s[0:1], vcc
	v_sub_u32_e32 v23, v106, v50
	v_lshl_add_u32 v23, v23, 2, s96
	ds_read_b32 v139, v23 offset:56
	s_or_b64 exec, exec, s[0:1]
	v_add_u32_e32 v23, 0xffffff8d, v0
	s_movk_i32 s0, 0x7f
	v_cmp_lt_u32_e32 vcc, s0, v23
	s_and_saveexec_b64 s[0:1], vcc
	s_xor_b64 s[0:1], exec, s[0:1]
	v_sub_u32_e32 v22, v106, v50
	s_or_saveexec_b64 s[0:1], s[0:1]
	v_mov_b32_e32 v140, 0xf1c9f2ca
	v_mov_b32_e32 v141, 0xf1c9f2ca
	s_xor_b64 exec, exec, s[0:1]
	v_lshl_add_u32 v23, v22, 2, s96
	ds_read_b32 v141, v23 offset:52
	s_or_b64 exec, exec, s[0:1]
	v_cmp_gt_u32_e32 vcc, s94, v22
	s_and_saveexec_b64 s[0:1], vcc
	v_lshl_add_u32 v23, v22, 2, s96
	ds_read_b32 v140, v23
	s_or_b64 exec, exec, s[0:1]
	v_add_u32_e32 v23, 0xffffff7f, v0
	v_cmp_gt_u32_e32 vcc, s94, v23
	v_mov_b32_e32 v142, 0xf1c9f2ca
	v_lshlrev_b32_e32 v22, 2, v22
	v_mov_b32_e32 v143, 0xf1c9f2ca
	s_and_saveexec_b64 s[0:1], vcc
	v_add3_u32 v23, v22, s96, -4
	ds_read_b32 v143, v23
	s_or_b64 exec, exec, s[0:1]
	v_add_u32_e32 v23, 0xffffff7e, v0
	v_cmp_gt_u32_e32 vcc, s94, v23
	s_and_saveexec_b64 s[0:1], vcc
	v_add3_u32 v23, v22, s96, -8
	ds_read_b32 v142, v23
	s_or_b64 exec, exec, s[0:1]
	v_add_u32_e32 v0, 0xffffff7d, v0
	v_cmp_gt_u32_e32 vcc, s94, v0
	v_mov_b32_e32 v144, 0xf1c9f2ca
	s_and_saveexec_b64 s[0:1], vcc
	v_add3_u32 v0, v22, s96, -12
	ds_read_b32 v144, v0
	s_or_b64 exec, exec, s[0:1]
	s_waitcnt lgkmcnt(2)
	v_pk_add_f32 v[18:19], v[18:19], v[20:21]
	s_mov_b32 s0, 0x3c800000
	v_pk_fma_f32 v[98:99], v[18:19], s[0:1], v[240:241] op_sel_hi:[1,0,0]
	s_mov_b32 s0, 0x800000
	v_mul_f32_e32 v0, 0x4b800000, v99
	v_cmp_gt_f32_e32 vcc, s0, v99
	v_readlane_b32 s10, v254, 43
	v_readlane_b32 s18, v254, 45
	v_cndmask_b32_e32 v0, v99, v0, vcc
	v_rsq_f32_e32 v0, v0
	v_lshlrev_b32_e32 v99, 1, v96
	v_cmp_gt_f32_e64 s[62:63], s0, v98
	s_and_b64 s[0:1], s[4:5], exec
	v_mul_f32_e32 v18, 0x45800000, v0
	v_cndmask_b32_e32 v0, v0, v18, vcc
	v_mul_f32_e32 v0, 0x3e000000, v0
	s_waitcnt vmcnt(3)
	v_pk_mul_f32 v[18:19], v[4:5], v[0:1] op_sel_hi:[1,0]
	s_waitcnt vmcnt(0)
	v_pk_mul_f32 v[22:23], v[16:17], v[0:1] op_sel_hi:[1,0]
	v_pk_mul_f32 v[18:19], v[18:19], v[104:105]
	v_pk_mul_f32 v[22:23], v[22:23], v[28:29]
	v_cvt_pk_bf16_f32 v21, v18, v19
	v_pk_mul_f32 v[18:19], v[8:9], v[0:1] op_sel_hi:[1,0]
	v_cvt_pk_bf16_f32 v39, v22, v23
	v_pk_mul_f32 v[18:19], v[18:19], v[100:101]
	v_pk_mul_f32 v[22:23], v[10:11], v[0:1] op_sel_hi:[1,0]
	v_cvt_pk_bf16_f32 v41, v18, v19
	v_pk_mul_f32 v[18:19], v[2:3], v[0:1] op_sel_hi:[1,0]
	v_pk_mul_f32 v[22:23], v[22:23], v[32:33]
	v_pk_mul_f32 v[18:19], v[18:19], v[102:103]
	s_cselect_b32 s92, 0, 0x80
	v_cvt_pk_bf16_f32 v20, v18, v19
	v_pk_mul_f32 v[18:19], v[6:7], v[0:1] op_sel_hi:[1,0]
	v_readlane_b32 s46, v255, 4
	v_pk_mul_f32 v[18:19], v[18:19], v[36:37]
	s_nop 0
	v_cvt_pk_bf16_f32 v40, v18, v19
	v_pk_mul_f32 v[18:19], v[12:13], v[0:1] op_sel_hi:[1,0]
	s_nop 0
	v_pk_mul_f32 v[18:19], v[18:19], v[24:25]
	s_nop 0
	v_cvt_pk_bf16_f32 v19, v18, v19
	v_cvt_pk_bf16_f32 v18, v22, v23
	v_pk_mul_f32 v[22:23], v[14:15], v[0:1] op_sel_hi:[1,0]
	v_or_b32_e32 v0, s88, v106
	v_mul_u32_u24_e32 v0, 0x90, v0
	v_pk_mul_f32 v[22:23], v[22:23], v[34:35]
	v_add3_u32 v0, 0, v0, v99
	v_cvt_pk_bf16_f32 v38, v22, v23
	ds_read_b128 v[22:25], v0
	ds_read_b128 v[26:29], v0 offset:64
	s_waitcnt lgkmcnt(1)
	v_mfma_f32_16x16x32_bf16 v[22:25], v[22:25], v[38:41], 0
	v_or_b32_e32 v0, s89, v106
	v_mul_u32_u24_e32 v0, 0x90, v0
	v_add3_u32 v146, 0, v0, v99
	s_waitcnt lgkmcnt(0)
	v_mfma_f32_16x16x32_bf16 v[148:151], v[26:29], v[18:21], v[22:25]
	ds_read_b128 v[26:29], v146 offset:64
	v_or_b32_e32 v0, s90, v106
	v_mul_u32_u24_e32 v0, 0x90, v0
	ds_read_b128 v[22:25], v146
	s_waitcnt lgkmcnt(0)
	v_mfma_f32_16x16x32_bf16 v[22:25], v[22:25], v[38:41], 0
	v_add3_u32 v145, 0, v0, v99
	v_or_b32_e32 v0, s91, v106
	v_mul_u32_u24_e32 v0, 0x90, v0
	v_mfma_f32_16x16x32_bf16 v[152:155], v[26:29], v[18:21], v[22:25]
	ds_read_b128 v[26:29], v145 offset:64
	v_add3_u32 v105, 0, v0, v99
	v_or_b32_e32 v0, s10, v106
	s_nop 0
	ds_read_b128 v[22:25], v145
	s_waitcnt lgkmcnt(0)
	v_mfma_f32_16x16x32_bf16 v[22:25], v[22:25], v[38:41], 0
	v_mul_u32_u24_e32 v0, 0x90, v0
	v_add3_u32 v100, 0, v0, v99
	v_or_b32_e32 v0, s18, v106
	v_mfma_f32_16x16x32_bf16 v[156:159], v[26:29], v[18:21], v[22:25]
	ds_read_b128 v[26:29], v105 offset:64
	v_mul_u32_u24_e32 v0, 0x90, v0
	v_add3_u32 v101, 0, v0, v99
	s_nop 0
	ds_read_b128 v[22:25], v105
	s_waitcnt lgkmcnt(0)
	v_mfma_f32_16x16x32_bf16 v[22:25], v[22:25], v[38:41], 0
	v_or_b32_e32 v0, s73, v106
	v_mul_u32_u24_e32 v0, 0x90, v0
	v_add3_u32 v102, 0, v0, v99
	v_mfma_f32_16x16x32_bf16 v[160:163], v[26:29], v[18:21], v[22:25]
	ds_read_b128 v[26:29], v100 offset:64
	v_or_b32_e32 v0, s74, v106
	v_mul_u32_u24_e32 v0, 0x90, v0
	s_nop 0
	ds_read_b128 v[22:25], v100
	s_waitcnt lgkmcnt(0)
	v_mfma_f32_16x16x32_bf16 v[22:25], v[22:25], v[38:41], 0
	v_add3_u32 v103, 0, v0, v99
	ds_read_b128 v[170:173], v103 offset:64
	v_or_b32_e32 v0, s75, v106
	v_mfma_f32_16x16x32_bf16 v[34:37], v[26:29], v[18:21], v[22:25]
	ds_read_b128 v[26:29], v101 offset:64
	v_mul_u32_u24_e32 v0, 0x90, v0
	v_add3_u32 v104, 0, v0, v99
	s_nop 0
	ds_read_b128 v[22:25], v101
	s_waitcnt lgkmcnt(0)
	v_mfma_f32_16x16x32_bf16 v[22:25], v[22:25], v[38:41], 0
	v_add_u32_e32 v0, s88, v50
	v_cmp_le_i32_e32 vcc, s92, v0
	v_or_b32_e32 v51, 2, v0
	v_mfma_f32_16x16x32_bf16 v[30:33], v[26:29], v[18:21], v[22:25]
	ds_read_b128 v[26:29], v102 offset:64
	v_add_f32_e32 v147, v114, v152
	v_add_f32_e32 v152, v117, v157
	s_nop 0
	ds_read_b128 v[22:25], v102
	s_waitcnt lgkmcnt(0)
	v_mfma_f32_16x16x32_bf16 v[22:25], v[22:25], v[38:41], 0
	v_max_f32_e32 v147, 0xf149f2ca, v147
	v_max_f32_e32 v152, 0xf149f2ca, v152
	v_add_f32_e32 v34, v126, v34
	v_mfma_f32_16x16x32_bf16 v[26:29], v[26:29], v[18:21], v[22:25]
	v_add_f32_e32 v35, v125, v35
	v_max_f32_e32 v34, 0xf149f2ca, v34
	v_max_f32_e32 v35, 0xf149f2ca, v35
	s_nop 0
	ds_read_b128 v[22:25], v103
	s_waitcnt lgkmcnt(0)
	v_mfma_f32_16x16x32_bf16 v[22:25], v[22:25], v[38:41], 0
	v_add_f32_e32 v36, v128, v36
	v_add_f32_e32 v37, v127, v37
	v_max_f32_e32 v36, 0xf149f2ca, v36
	v_mfma_f32_16x16x32_bf16 v[22:25], v[170:173], v[18:21], v[22:25]
	ds_read_b128 v[170:173], v104
	v_max_f32_e32 v37, 0xf149f2ca, v37
	v_add_f32_e32 v30, v130, v30
	s_waitcnt lgkmcnt(0)
	v_mfma_f32_16x16x32_bf16 v[38:41], v[170:173], v[38:41], 0
	ds_read_b128 v[170:173], v104 offset:64
	v_add_f32_e32 v31, v129, v31
	v_max_f32_e32 v30, 0xf149f2ca, v30
	s_waitcnt lgkmcnt(0)
	v_mfma_f32_16x16x32_bf16 v[18:21], v[170:173], v[18:21], v[38:41]
	s_nop 2
	v_add_f32_e32 v38, v110, v148
	v_max_f32_e32 v38, 0xf149f2ca, v38
	v_cndmask_b32_e32 v39, v212, v38, vcc
	v_add_f32_e32 v38, v109, v149
	v_or_b32_e32 v40, 1, v0
	v_max_f32_e32 v38, 0xf149f2ca, v38
	v_cmp_le_i32_e32 vcc, s92, v40
	v_add_f32_e32 v41, v112, v150
	v_max_f32_e32 v41, 0xf149f2ca, v41
	v_cndmask_b32_e32 v40, v212, v38, vcc
	v_cmp_le_i32_e32 vcc, s92, v51
	v_or_b32_e32 v0, 3, v0
	v_add_f32_e32 v148, v113, v153
	v_cndmask_b32_e32 v51, v212, v41, vcc
	v_add_f32_e32 v41, v111, v151
	v_max_f32_e32 v41, 0xf149f2ca, v41
	v_cmp_le_i32_e32 vcc, s92, v0
	v_max3_f32 v38, v97, v39, v40
	v_max_f32_e32 v148, 0xf149f2ca, v148
	v_cndmask_b32_e32 v0, v212, v41, vcc
	v_add_u32_e32 v41, s89, v50
	v_or_b32_e32 v150, 2, v41
	v_cmp_gt_i32_e64 s[64:65], s92, v41
	v_or_b32_e32 v149, 1, v41
	v_cmp_gt_i32_e64 s[68:69], s92, v150
	v_add_f32_e32 v150, v115, v155
	v_or_b32_e32 v41, 3, v41
	v_cmp_gt_i32_e64 s[70:71], s92, v41
	v_max_f32_e32 v41, 0xf149f2ca, v150
	v_cmp_gt_i32_e64 s[66:67], s92, v149
	v_cndmask_b32_e64 v150, v41, v212, s[70:71]
	v_add_u32_e32 v41, s90, v50
	v_add_f32_e32 v149, v116, v154
	v_or_b32_e32 v154, 2, v41
	v_cmp_gt_i32_e64 s[54:55], s92, v41
	v_or_b32_e32 v153, 1, v41
	v_cmp_gt_i32_e64 s[58:59], s92, v154
	v_add_f32_e32 v154, v119, v159
	v_or_b32_e32 v41, 3, v41
	v_cmp_gt_i32_e64 s[60:61], s92, v41
	v_max_f32_e32 v41, 0xf149f2ca, v154
	v_cmp_gt_i32_e64 s[56:57], s92, v153
	v_cndmask_b32_e64 v154, v41, v212, s[60:61]
	v_add_u32_e32 v41, s91, v50
	v_add_f32_e32 v153, v120, v158
	v_or_b32_e32 v158, 2, v41
	v_cmp_gt_i32_e64 s[0:1], s92, v41
	v_or_b32_e32 v157, 1, v41
	v_cmp_gt_i32_e64 s[6:7], s92, v158
	v_add_f32_e32 v158, v123, v163
	v_or_b32_e32 v41, 3, v41
	v_cmp_gt_i32_e64 s[8:9], s92, v41
	v_max_f32_e32 v41, 0xf149f2ca, v158
	v_max3_f32 v38, v38, v51, v0
	v_cndmask_b32_e64 v158, v41, v212, s[8:9]
	v_add_u32_e32 v41, s10, v50
	v_or_b32_e32 v159, 1, v41
	v_cmp_gt_i32_e64 s[10:11], s92, v41
	v_cmp_gt_i32_e64 s[12:13], s92, v159
	v_or_b32_e32 v159, 2, v41
	v_or_b32_e32 v41, 3, v41
	v_cmp_gt_i32_e64 s[16:17], s92, v41
	v_add_u32_e32 v41, s18, v50
	v_cndmask_b32_e64 v147, v147, v212, s[64:65]
	v_cndmask_b32_e64 v148, v148, v212, s[66:67]
	v_max_f32_e32 v149, 0xf149f2ca, v149
	v_add_f32_e32 v151, v118, v156
	v_cmp_gt_i32_e64 s[14:15], s92, v159
	v_or_b32_e32 v159, 1, v41
	v_max3_f32 v38, v38, v147, v148
	v_cndmask_b32_e64 v149, v149, v212, s[68:69]
	v_max_f32_e32 v151, 0xf149f2ca, v151
	v_cmp_gt_i32_e64 s[18:19], s92, v41
	v_cmp_gt_i32_e64 s[20:21], s92, v159
	v_or_b32_e32 v159, 2, v41
	v_or_b32_e32 v41, 3, v41
	v_max3_f32 v38, v38, v149, v150
	v_cndmask_b32_e64 v151, v151, v212, s[54:55]
	v_cndmask_b32_e64 v152, v152, v212, s[56:57]
	v_max_f32_e32 v153, 0xf149f2ca, v153
	v_add_f32_e32 v155, v122, v160
	v_add_f32_e32 v156, v121, v161
	v_cmp_gt_i32_e64 s[24:25], s92, v41
	v_add_u32_e32 v41, s73, v50
	v_max3_f32 v38, v38, v151, v152
	v_cndmask_b32_e64 v153, v153, v212, s[58:59]
	v_max_f32_e32 v155, 0xf149f2ca, v155
	v_cmp_gt_i32_e64 s[4:5], s92, v157
	v_max_f32_e32 v156, 0xf149f2ca, v156
	v_add_f32_e32 v157, v124, v162
	v_cmp_gt_i32_e64 s[22:23], s92, v159
	v_or_b32_e32 v159, 1, v41
	v_max3_f32 v38, v38, v153, v154
	v_cndmask_b32_e64 v155, v155, v212, s[0:1]
	v_cndmask_b32_e64 v156, v156, v212, s[4:5]
	v_max_f32_e32 v157, 0xf149f2ca, v157
	v_cmp_gt_i32_e64 s[26:27], s92, v41
	v_cmp_gt_i32_e64 s[28:29], s92, v159
	v_or_b32_e32 v159, 2, v41
	v_or_b32_e32 v41, 3, v41
	v_max3_f32 v38, v38, v155, v156
	v_cndmask_b32_e64 v157, v157, v212, s[6:7]
	v_cmp_gt_i32_e64 s[34:35], s92, v41
	v_add_u32_e32 v41, s74, v50
	v_max3_f32 v38, v38, v157, v158
	v_cndmask_b32_e64 v34, v34, v212, s[10:11]
	v_cndmask_b32_e64 v35, v35, v212, s[12:13]
	v_cmp_gt_i32_e64 s[30:31], s92, v159
	v_or_b32_e32 v159, 1, v41
	v_max3_f32 v38, v38, v34, v35
	v_cndmask_b32_e64 v36, v36, v212, s[14:15]
	v_cndmask_b32_e64 v37, v37, v212, s[16:17]
	v_max_f32_e32 v31, 0xf149f2ca, v31
	v_add_f32_e32 v32, v132, v32
	v_add_f32_e32 v33, v131, v33
	v_cmp_gt_i32_e64 s[36:37], s92, v41
	v_cmp_gt_i32_e64 s[38:39], s92, v159
	v_or_b32_e32 v159, 2, v41
	v_or_b32_e32 v41, 3, v41
	v_max3_f32 v38, v38, v36, v37
	v_cndmask_b32_e64 v30, v30, v212, s[18:19]
	v_cndmask_b32_e64 v31, v31, v212, s[20:21]
	v_max_f32_e32 v32, 0xf149f2ca, v32
	v_max_f32_e32 v33, 0xf149f2ca, v33
	v_add_f32_e32 v26, v134, v26
	v_add_f32_e32 v27, v133, v27
	v_cmp_gt_i32_e64 s[42:43], s92, v41
	v_add_u32_e32 v41, s75, v50
	v_add_f32_e32 v18, v140, v18
	v_max3_f32 v38, v38, v30, v31
	v_cndmask_b32_e64 v32, v32, v212, s[22:23]
	v_cndmask_b32_e64 v33, v33, v212, s[24:25]
	v_max_f32_e32 v26, 0xf149f2ca, v26
	v_max_f32_e32 v27, 0xf149f2ca, v27
	v_add_f32_e32 v28, v136, v28
	v_add_f32_e32 v29, v135, v29
	v_cmp_gt_i32_e64 s[44:45], s92, v41
	v_max_f32_e32 v18, 0xf149f2ca, v18
	v_max3_f32 v38, v38, v32, v33
	v_cndmask_b32_e64 v26, v26, v212, s[26:27]
	v_cndmask_b32_e64 v27, v27, v212, s[28:29]
	v_max_f32_e32 v28, 0xf149f2ca, v28
	v_max_f32_e32 v29, 0xf149f2ca, v29
	v_add_f32_e32 v22, v138, v22
	v_add_f32_e32 v23, v137, v23
	v_cmp_gt_i32_e64 s[40:41], s92, v159
	v_cndmask_b32_e64 v159, v18, v212, s[44:45]
	v_add_f32_e32 v18, v143, v19
	v_or_b32_e32 v19, 1, v41
	v_max3_f32 v38, v38, v26, v27
	v_cndmask_b32_e64 v28, v28, v212, s[30:31]
	v_cndmask_b32_e64 v29, v29, v212, s[34:35]
	v_max_f32_e32 v22, 0xf149f2ca, v22
	v_max_f32_e32 v23, 0xf149f2ca, v23
	v_add_f32_e32 v24, v139, v24
	v_add_f32_e32 v25, v141, v25
	v_cmp_gt_i32_e64 s[48:49], s92, v19
	v_add_f32_e32 v19, v142, v20
	v_or_b32_e32 v20, 2, v41
	v_max3_f32 v38, v38, v28, v29
	v_cndmask_b32_e64 v22, v22, v212, s[36:37]
	v_cndmask_b32_e64 v23, v23, v212, s[38:39]
	v_max_f32_e32 v24, 0xf149f2ca, v24
	v_max_f32_e32 v25, 0xf149f2ca, v25
	v_cmp_gt_i32_e64 s[50:51], s92, v20
	v_max_f32_e32 v19, 0xf149f2ca, v19
	v_max3_f32 v38, v38, v22, v23
	v_cndmask_b32_e64 v24, v24, v212, s[40:41]
	v_cndmask_b32_e64 v25, v25, v212, s[42:43]
	v_max_f32_e32 v18, 0xf149f2ca, v18
	v_cndmask_b32_e64 v161, v19, v212, s[50:51]
	v_add_f32_e32 v19, v144, v21
	v_or_b32_e32 v20, 3, v41
	v_max3_f32 v38, v38, v24, v25
	v_cndmask_b32_e64 v160, v18, v212, s[48:49]
	v_cmp_gt_i32_e64 s[52:53], s92, v20
	v_max_f32_e32 v19, 0xf149f2ca, v19
	v_max3_f32 v18, v38, v159, v160
	v_cndmask_b32_e64 v162, v19, v212, s[52:53]
	v_max3_f32 v18, v18, v161, v162
	ds_bpermute_b32 v19, v107, v18
	s_andn2_b64 vcc, exec, s[76:77]
	s_waitcnt lgkmcnt(0)
	v_max_f32_e32 v19, v19, v19
	v_max_f32_e32 v18, v18, v19
	ds_bpermute_b32 v19, v108, v18
	s_waitcnt lgkmcnt(0)
	v_max_f32_e32 v19, v19, v19
	v_max_f32_e32 v41, v18, v19
	v_mul_u32_u24_e32 v18, 0x150, v106
	v_add3_u32 v38, s46, v18, v96
	v_sub_f32_e32 v18, v39, v41
	v_mul_f32_e32 v18, 0x3fb8aa3b, v18
	v_sub_f32_e32 v20, v40, v41
	v_exp_f32_e32 v18, v18
	v_mul_f32_e32 v20, 0x3fb8aa3b, v20
	v_sub_f32_e32 v21, v51, v41
	v_exp_f32_e32 v20, v20
	v_mul_f32_e32 v21, 0x3fb8aa3b, v21
	v_sub_f32_e32 v0, v0, v41
	v_exp_f32_e32 v21, v21
	v_mul_f32_e32 v0, 0x3fb8aa3b, v0
	v_exp_f32_e32 v0, v0
	v_add_f32_e32 v19, 0, v18
	v_add_f32_e32 v19, v20, v19
	v_add_f32_e32 v19, v21, v19
	v_add_f32_e32 v39, v0, v19
	v_cvt_pk_bf16_f32 v19, v21, v0
	v_sub_f32_e32 v0, v147, v41
	v_mul_f32_e32 v0, 0x3fb8aa3b, v0
	v_exp_f32_e32 v0, v0
	v_sub_f32_e32 v21, v148, v41
	v_cvt_pk_bf16_f32 v18, v18, v20
	v_mul_f32_e32 v21, 0x3fb8aa3b, v21
	v_add_f32_e32 v20, v0, v39
	v_sub_f32_e32 v39, v149, v41
	v_exp_f32_e32 v21, v21
	v_mul_f32_e32 v39, 0x3fb8aa3b, v39
	v_sub_f32_e32 v40, v150, v41
	v_exp_f32_e32 v39, v39
	v_mul_f32_e32 v40, 0x3fb8aa3b, v40
	v_exp_f32_e32 v40, v40
	v_add_f32_e32 v20, v21, v20
	v_add_f32_e32 v20, v39, v20
	v_readlane_b32 s46, v254, 47
	v_add_f32_e32 v51, v40, v20
	v_cvt_pk_bf16_f32 v20, v0, v21
	v_cvt_pk_bf16_f32 v21, v39, v40
	v_sub_f32_e32 v0, v151, v41
	ds_write2_b64 v38, v[18:19], v[20:21] offset1:4
	v_mul_f32_e32 v0, 0x3fb8aa3b, v0
	v_sub_f32_e32 v19, v152, v41
	v_exp_f32_e32 v0, v0
	v_mul_f32_e32 v19, 0x3fb8aa3b, v19
	v_sub_f32_e32 v20, v153, v41
	v_exp_f32_e32 v19, v19
	v_mul_f32_e32 v20, 0x3fb8aa3b, v20
	v_sub_f32_e32 v21, v154, v41
	v_exp_f32_e32 v20, v20
	v_mul_f32_e32 v21, 0x3fb8aa3b, v21
	v_exp_f32_e32 v21, v21
	v_add_f32_e32 v18, v0, v51
	v_add_f32_e32 v18, v19, v18
	v_add_f32_e32 v18, v20, v18
	v_add_f32_e32 v39, v21, v18
	v_cvt_pk_bf16_f32 v18, v0, v19
	v_sub_f32_e32 v0, v155, v41
	v_mul_f32_e32 v0, 0x3fb8aa3b, v0
	v_exp_f32_e32 v0, v0
	v_cvt_pk_bf16_f32 v19, v20, v21
	v_sub_f32_e32 v21, v156, v41
	v_mul_f32_e32 v21, 0x3fb8aa3b, v21
	v_add_f32_e32 v20, v0, v39
	v_sub_f32_e32 v39, v157, v41
	v_exp_f32_e32 v21, v21
	v_mul_f32_e32 v39, 0x3fb8aa3b, v39
	v_sub_f32_e32 v40, v158, v41
	v_exp_f32_e32 v39, v39
	v_mul_f32_e32 v40, 0x3fb8aa3b, v40
	v_exp_f32_e32 v40, v40
	v_add_f32_e32 v20, v21, v20
	v_add_f32_e32 v20, v39, v20
	v_add_f32_e32 v51, v40, v20
	v_cvt_pk_bf16_f32 v20, v0, v21
	v_cvt_pk_bf16_f32 v21, v39, v40
	v_sub_f32_e32 v0, v34, v41
	ds_write2_b64 v38, v[18:19], v[20:21] offset0:8 offset1:12
	v_mul_f32_e32 v0, 0x3fb8aa3b, v0
	v_sub_f32_e32 v19, v35, v41
	v_exp_f32_e32 v0, v0
	v_mul_f32_e32 v19, 0x3fb8aa3b, v19
	v_sub_f32_e32 v20, v36, v41
	v_exp_f32_e32 v19, v19
	v_mul_f32_e32 v20, 0x3fb8aa3b, v20
	v_sub_f32_e32 v21, v37, v41
	v_exp_f32_e32 v20, v20
	v_mul_f32_e32 v21, 0x3fb8aa3b, v21
	v_exp_f32_e32 v21, v21
	v_add_f32_e32 v18, v0, v51
	v_add_f32_e32 v18, v19, v18
	v_add_f32_e32 v18, v20, v18
	v_add_f32_e32 v34, v21, v18
	v_cvt_pk_bf16_f32 v18, v0, v19
	v_sub_f32_e32 v0, v30, v41
	v_cvt_pk_bf16_f32 v19, v20, v21
	v_mul_f32_e32 v0, 0x3fb8aa3b, v0
	v_sub_f32_e32 v21, v31, v41
	v_exp_f32_e32 v0, v0
	v_mul_f32_e32 v21, 0x3fb8aa3b, v21
	v_sub_f32_e32 v30, v32, v41
	v_exp_f32_e32 v21, v21
	v_mul_f32_e32 v30, 0x3fb8aa3b, v30
	v_sub_f32_e32 v31, v33, v41
	v_exp_f32_e32 v30, v30
	v_mul_f32_e32 v31, 0x3fb8aa3b, v31
	v_exp_f32_e32 v31, v31
	v_add_f32_e32 v20, v0, v34
	v_add_f32_e32 v20, v21, v20
	v_add_f32_e32 v20, v30, v20
	v_add_f32_e32 v32, v31, v20
	v_cvt_pk_bf16_f32 v20, v0, v21
	v_cvt_pk_bf16_f32 v21, v30, v31
	v_sub_f32_e32 v0, v26, v41
	ds_write2_b64 v38, v[18:19], v[20:21] offset0:16 offset1:20
	v_mul_f32_e32 v0, 0x3fb8aa3b, v0
	v_sub_f32_e32 v19, v27, v41
	v_exp_f32_e32 v0, v0
	v_mul_f32_e32 v19, 0x3fb8aa3b, v19
	v_sub_f32_e32 v20, v28, v41
	v_exp_f32_e32 v19, v19
	v_mul_f32_e32 v20, 0x3fb8aa3b, v20
	v_sub_f32_e32 v21, v29, v41
	v_exp_f32_e32 v20, v20
	v_mul_f32_e32 v21, 0x3fb8aa3b, v21
	v_exp_f32_e32 v21, v21
	v_add_f32_e32 v18, v0, v32
	v_add_f32_e32 v18, v19, v18
	v_add_f32_e32 v18, v20, v18
	v_add_f32_e32 v26, v21, v18
	v_cvt_pk_bf16_f32 v18, v0, v19
	v_sub_f32_e32 v0, v22, v41
	v_cvt_pk_bf16_f32 v19, v20, v21
	v_mul_f32_e32 v0, 0x3fb8aa3b, v0
	v_sub_f32_e32 v21, v23, v41
	v_exp_f32_e32 v0, v0
	v_mul_f32_e32 v21, 0x3fb8aa3b, v21
	v_sub_f32_e32 v22, v24, v41
	v_exp_f32_e32 v21, v21
	v_mul_f32_e32 v22, 0x3fb8aa3b, v22
	v_sub_f32_e32 v23, v25, v41
	v_exp_f32_e32 v22, v22
	v_mul_f32_e32 v23, 0x3fb8aa3b, v23
	v_exp_f32_e32 v23, v23
	v_add_f32_e32 v20, v0, v26
	v_add_f32_e32 v20, v21, v20
	v_add_f32_e32 v20, v22, v20
	v_add_f32_e32 v24, v23, v20
	v_cvt_pk_bf16_f32 v20, v0, v21
	v_cvt_pk_bf16_f32 v21, v22, v23
	v_sub_f32_e32 v0, v159, v41
	ds_write2_b64 v38, v[18:19], v[20:21] offset0:24 offset1:28
	v_mul_f32_e32 v0, 0x3fb8aa3b, v0
	v_sub_f32_e32 v19, v160, v41
	v_exp_f32_e32 v0, v0
	v_mul_f32_e32 v19, 0x3fb8aa3b, v19
	v_sub_f32_e32 v20, v161, v41
	v_exp_f32_e32 v19, v19
	v_mul_f32_e32 v20, 0x3fb8aa3b, v20
	v_sub_f32_e32 v21, v162, v41
	v_exp_f32_e32 v20, v20
	v_mul_f32_e32 v21, 0x3fb8aa3b, v21
	v_exp_f32_e32 v21, v21
	v_add_f32_e32 v18, v0, v24
	v_add_f32_e32 v18, v19, v18
	v_add_f32_e32 v18, v20, v18
	v_add_f32_e32 v22, v21, v18
	v_cvt_pk_bf16_f32 v18, v0, v19
	v_cvt_pk_bf16_f32 v19, v20, v21
	v_mov_b32_e32 v0, v1
	ds_write2_b64 v38, v[18:19], v[0:1] offset0:32 offset1:36
	ds_bpermute_b32 v18, v107, v22
	v_mul_u32_u24_e32 v40, 0x230, v106
	v_add_u32_e32 v39, v38, v96
	v_add3_u32 v51, s46, v99, v40
	ds_read_b128 v[26:29], v51 offset:45824
	ds_read_b128 v[30:33], v51 offset:54784
	s_waitcnt lgkmcnt(2)
	v_add_f32_e32 v147, v22, v18
	ds_read_b128 v[18:21], v39
	ds_read_b128 v[22:25], v51 offset:36864
	ds_read_b128 v[34:37], v51 offset:63744
	s_waitcnt lgkmcnt(1)
	v_mfma_f32_16x16x32_bf16 v[22:25], v[22:25], v[18:21], 0
	ds_bpermute_b32 v148, v108, v147
	v_mfma_f32_16x16x32_bf16 v[26:29], v[26:29], v[18:21], 0
	v_mfma_f32_16x16x32_bf16 v[30:33], v[30:33], v[18:21], 0
	s_waitcnt lgkmcnt(1)
	v_mfma_f32_16x16x32_bf16 v[18:21], v[34:37], v[18:21], 0
	ds_read_b128 v[34:37], v39 offset:64
	ds_read_b128 v[150:153], v51 offset:36928
	s_waitcnt lgkmcnt(0)
	v_mfma_f32_16x16x32_bf16 v[22:25], v[150:153], v[34:37], v[22:25]
	ds_read_b128 v[150:153], v51 offset:45888
	s_waitcnt lgkmcnt(0)
	v_mfma_f32_16x16x32_bf16 v[26:29], v[150:153], v[34:37], v[26:29]
	ds_read_b128 v[150:153], v51 offset:54848
	s_waitcnt lgkmcnt(0)
	v_mfma_f32_16x16x32_bf16 v[30:33], v[150:153], v[34:37], v[30:33]
	ds_read_b128 v[150:153], v51 offset:63808
	s_waitcnt lgkmcnt(0)
	v_mfma_f32_16x16x32_bf16 v[18:21], v[150:153], v[34:37], v[18:21]
	ds_read_b128 v[34:37], v39 offset:128
	ds_read_b128 v[150:153], v51 offset:36992
	s_waitcnt lgkmcnt(0)
	v_mfma_f32_16x16x32_bf16 v[22:25], v[150:153], v[34:37], v[22:25]
	ds_read_b128 v[150:153], v51 offset:45952
	s_waitcnt lgkmcnt(0)
	v_mfma_f32_16x16x32_bf16 v[26:29], v[150:153], v[34:37], v[26:29]
	ds_read_b128 v[150:153], v51 offset:54912
	s_waitcnt lgkmcnt(0)
	v_mfma_f32_16x16x32_bf16 v[30:33], v[150:153], v[34:37], v[30:33]
	ds_read_b128 v[150:153], v51 offset:63872
	s_waitcnt lgkmcnt(0)
	v_mfma_f32_16x16x32_bf16 v[18:21], v[150:153], v[34:37], v[18:21]
	ds_read_b128 v[34:37], v39 offset:192
	ds_read_b128 v[150:153], v51 offset:37056
	s_waitcnt lgkmcnt(0)
	v_mfma_f32_16x16x32_bf16 v[22:25], v[150:153], v[34:37], v[22:25]
	ds_read_b128 v[150:153], v51 offset:46016
	s_waitcnt lgkmcnt(0)
	v_mfma_f32_16x16x32_bf16 v[150:153], v[150:153], v[34:37], v[26:29]
	s_nop 2
	ds_read_b128 v[26:29], v51 offset:54976
	s_waitcnt lgkmcnt(0)
	v_mfma_f32_16x16x32_bf16 v[26:29], v[26:29], v[34:37], v[30:33]
	s_nop 2
	ds_read_b128 v[30:33], v51 offset:63936
	s_waitcnt lgkmcnt(0)
	v_mfma_f32_16x16x32_bf16 v[18:21], v[30:33], v[34:37], v[18:21]
	ds_read_b128 v[34:37], v39 offset:256
	ds_read_b128 v[30:33], v51 offset:37120
	s_waitcnt lgkmcnt(0)
	v_mfma_f32_16x16x32_bf16 v[22:25], v[30:33], v[34:37], v[22:25]
	ds_read_b128 v[30:33], v51 offset:46080
	s_waitcnt lgkmcnt(0)
	v_mfma_f32_16x16x32_bf16 v[30:33], v[30:33], v[34:37], v[150:153]
	s_nop 2
	ds_read_b128 v[150:153], v51 offset:55040
	s_waitcnt lgkmcnt(0)
	v_mfma_f32_16x16x32_bf16 v[26:29], v[150:153], v[34:37], v[26:29]
	ds_read_b128 v[150:153], v51 offset:64000
	v_ashrrev_i32_e32 v51, 31, v50
	s_waitcnt lgkmcnt(0)
	v_mfma_f32_16x16x32_bf16 v[18:21], v[150:153], v[34:37], v[18:21]
	v_cndmask_b32_e64 v34, 0, 1, s[76:77]
	v_cmp_ne_u32_e64 s[46:47], 1, v34
	s_cbranch_vccnz .LBB0_268
	v_sub_f32_e32 v37, v97, v41
	s_or_b32 s94, s78, s88
	v_mul_f32_e32 v37, 0x3fb8aa3b, v37
	v_or_b32_e32 v36, s94, v106
	v_readlane_b32 s94, v254, 32
	v_exp_f32_e32 v37, v37
	v_readlane_b32 s95, v254, 33
	s_nop 1
	v_mov_b64_e32 v[34:35], s[94:95]
	s_movk_i32 s94, 0x1c00
	v_mad_u64_u32 v[34:35], s[94:95], v36, s94, v[34:35]
	v_add_f32_e32 v36, v147, v148
	v_add_f32_e32 v36, v37, v36
	v_div_scale_f32 v37, s[94:95], v36, v36, 1.0
	v_rcp_f32_e32 v41, v37
	v_mad_i32_i24 v35, s79, v210, v35
	v_lshl_add_u64 v[34:35], s[2:3], 1, v[34:35]
	v_lshl_add_u64 v[34:35], v[50:51], 1, v[34:35]
	v_fma_f32 v96, -v37, v41, 1.0
	v_fmac_f32_e32 v41, v96, v41
	v_div_scale_f32 v96, vcc, 1.0, v36, 1.0
	v_mul_f32_e32 v147, v96, v41
	v_fma_f32 v148, -v37, v147, v96
	v_fmac_f32_e32 v147, v148, v41
	v_fma_f32 v37, -v37, v147, v96
	v_div_fmas_f32 v37, v37, v41, v147
	v_div_fixup_f32 v36, v37, v36, 1.0
	v_pk_mul_f32 v[24:25], v[24:25], v[36:37] op_sel_hi:[1,0]
	v_pk_mul_f32 v[22:23], v[22:23], v[36:37] op_sel_hi:[1,0]
	v_pk_mul_f32 v[32:33], v[32:33], v[36:37] op_sel_hi:[1,0]
	v_pk_mul_f32 v[30:31], v[30:31], v[36:37] op_sel_hi:[1,0]
	v_cvt_pk_bf16_f32 v22, v22, v23
	v_cvt_pk_bf16_f32 v23, v24, v25
	v_pk_mul_f32 v[20:21], v[36:37], v[20:21] op_sel_hi:[0,1]
	v_pk_mul_f32 v[18:19], v[36:37], v[18:19] op_sel_hi:[0,1]
	v_pk_mul_f32 v[28:29], v[36:37], v[28:29] op_sel_hi:[0,1]
	v_pk_mul_f32 v[26:27], v[36:37], v[26:27] op_sel_hi:[0,1]
	global_store_dwordx2 v[34:35], v[22:23], off offset:2048
	v_cvt_pk_bf16_f32 v22, v30, v31
	v_cvt_pk_bf16_f32 v23, v32, v33
	s_movk_i32 s95, 0x1c00
	s_movk_i32 s94, 0x80
	global_store_dwordx2 v[34:35], v[22:23], off offset:2080
	v_cvt_pk_bf16_f32 v22, v26, v27
	v_cvt_pk_bf16_f32 v23, v28, v29
	v_cvt_pk_bf16_f32 v18, v18, v19
	v_cvt_pk_bf16_f32 v19, v20, v21
	global_store_dwordx2 v[34:35], v[22:23], off offset:2112
	global_store_dwordx2 v[34:35], v[18:19], off offset:2144
